# v17 + non-temporal stores for the mlp-up output U (written once, read once by the next GEMM)
# speedup vs baseline: 1.0001x; 1.0001x over previous
.LBB0_108:
	v_mov_b32_e32 v142, v144
	v_mov_b32_e32 v143, v145
	s_lshl_b32 s4, s22, 8
	s_add_i32 s4, s4, s40
	v_add_u32_e32 v142, s4, v142
	s_lshl_b32 s4, s47, 8
	s_or_b32 s4, s4, s41
	v_lshl_add_u32 v148, v143, 3, s4
	v_ashrrev_i32_e32 v143, 31, v142
	v_lshlrev_b64 v[142:143], 13, v[142:143]
	v_max_f32_e32 v124, v124, v124
	v_max_f32_e32 v125, v125, v125
	v_ashrrev_i32_e32 v149, 31, v148
	v_lshl_add_u64 v[142:143], s[10:11], 0, v[142:143]
	v_max_f32_e32 v124, 0, v124
	v_max_f32_e32 v125, 0, v125
	v_lshl_add_u64 v[142:143], v[148:149], 1, v[142:143]
	v_pk_mul_f32 v[148:149], v[124:125], v[124:125]
	v_max_f32_e32 v125, v126, v126
	v_max_f32_e32 v128, v128, v128
	v_max_f32_e32 v129, v129, v129
	v_max_f32_e32 v124, v130, v130
	v_max_f32_e32 v126, 0, v125
	v_max_f32_e32 v125, v131, v131
	v_max_f32_e32 v127, v127, v127
	v_max_f32_e32 v128, 0, v128
	v_max_f32_e32 v129, 0, v129
	v_max_f32_e32 v124, 0, v124
	v_max_f32_e32 v125, 0, v125
	v_max_f32_e32 v127, 0, v127
	v_pk_mul_f32 v[128:129], v[128:129], v[128:129]
	v_pk_mul_f32 v[130:131], v[124:125], v[124:125]
	v_pk_mul_f32 v[150:151], v[126:127], v[126:127]
	v_max_f32_e32 v116, v116, v116
	v_max_f32_e32 v117, v117, v117
	v_cvt_pk_bf16_f32 v124, v128, v129
	v_cvt_pk_bf16_f32 v125, v130, v131
	v_cvt_pk_bf16_f32 v126, v148, v149
	v_cvt_pk_bf16_f32 v127, v150, v151
	v_max_f32_e32 v116, 0, v116
	v_max_f32_e32 v117, 0, v117
	global_store_dwordx4 v[142:143], v[124:127], off nt
	v_max_f32_e32 v120, v120, v120
	v_max_f32_e32 v121, v121, v121
	v_pk_mul_f32 v[124:125], v[116:117], v[116:117]
	v_max_f32_e32 v117, v118, v118
	v_max_f32_e32 v116, v122, v122
	v_max_f32_e32 v118, 0, v117
	v_max_f32_e32 v117, v123, v123
	v_max_f32_e32 v119, v119, v119
	v_max_f32_e32 v120, 0, v120
	v_max_f32_e32 v121, 0, v121
	v_max_f32_e32 v116, 0, v116
	v_max_f32_e32 v117, 0, v117
	v_max_f32_e32 v119, 0, v119
	v_pk_mul_f32 v[120:121], v[120:121], v[120:121]
	v_pk_mul_f32 v[122:123], v[116:117], v[116:117]
	v_pk_mul_f32 v[126:127], v[118:119], v[118:119]
	v_max_f32_e32 v108, v108, v108
	v_max_f32_e32 v109, v109, v109
	v_cvt_pk_bf16_f32 v116, v120, v121
	v_cvt_pk_bf16_f32 v117, v122, v123
	v_cvt_pk_bf16_f32 v118, v124, v125
	v_cvt_pk_bf16_f32 v119, v126, v127
	v_max_f32_e32 v108, 0, v108
	v_max_f32_e32 v109, 0, v109
	global_store_dwordx4 v[142:143], v[116:119], off offset:256 nt
	v_max_f32_e32 v112, v112, v112
	v_max_f32_e32 v113, v113, v113
	v_pk_mul_f32 v[118:119], v[108:109], v[108:109]
	v_max_f32_e32 v109, v110, v110
	s_mov_b64 s[4:5], 0x20000
	v_max_f32_e32 v112, 0, v112
	v_max_f32_e32 v113, 0, v113
	v_max_f32_e32 v108, v114, v114
	v_max_f32_e32 v110, 0, v109
	v_max_f32_e32 v109, v115, v115
	v_max_f32_e32 v111, v111, v111
	v_lshl_add_u64 v[116:117], v[142:143], 0, s[4:5]
	v_pk_mul_f32 v[112:113], v[112:113], v[112:113]
	v_max_f32_e32 v108, 0, v108
	v_max_f32_e32 v109, 0, v109
	v_max_f32_e32 v111, 0, v111
	s_mov_b32 s4, 0x20000
	v_pk_mul_f32 v[114:115], v[108:109], v[108:109]
	v_pk_mul_f32 v[120:121], v[110:111], v[110:111]
	v_cvt_pk_bf16_f32 v108, v112, v113
	v_add_co_u32_e32 v112, vcc, s4, v142
	v_max_f32_e32 v100, v100, v100
	v_max_f32_e32 v101, v101, v101
	v_cvt_pk_bf16_f32 v109, v114, v115
	v_cvt_pk_bf16_f32 v110, v118, v119
	v_cvt_pk_bf16_f32 v111, v120, v121
	v_addc_co_u32_e32 v113, vcc, 0, v143, vcc
	v_max_f32_e32 v100, 0, v100
	v_max_f32_e32 v101, 0, v101
	global_store_dwordx4 v[112:113], v[108:111], off nt
	v_max_f32_e32 v104, v104, v104
	v_max_f32_e32 v105, v105, v105
	v_pk_mul_f32 v[108:109], v[100:101], v[100:101]
	v_max_f32_e32 v101, v102, v102
	v_max_f32_e32 v100, v106, v106
	v_max_f32_e32 v102, 0, v101
	v_max_f32_e32 v101, v107, v107
	v_max_f32_e32 v103, v103, v103
	v_max_f32_e32 v104, 0, v104
	v_max_f32_e32 v105, 0, v105
	v_max_f32_e32 v100, 0, v100
	v_max_f32_e32 v101, 0, v101
	v_max_f32_e32 v103, 0, v103
	v_pk_mul_f32 v[104:105], v[104:105], v[104:105]
	v_pk_mul_f32 v[106:107], v[100:101], v[100:101]
	v_pk_mul_f32 v[110:111], v[102:103], v[102:103]
	v_max_f32_e32 v92, v92, v92
	v_max_f32_e32 v93, v93, v93
	v_cvt_pk_bf16_f32 v100, v104, v105
	v_cvt_pk_bf16_f32 v101, v106, v107
	v_cvt_pk_bf16_f32 v102, v108, v109
	v_cvt_pk_bf16_f32 v103, v110, v111
	v_max_f32_e32 v92, 0, v92
	v_max_f32_e32 v93, 0, v93
	global_store_dwordx4 v[116:117], v[100:103], off offset:256 nt
	v_max_f32_e32 v96, v96, v96
	v_max_f32_e32 v97, v97, v97
	v_pk_mul_f32 v[102:103], v[92:93], v[92:93]
	v_max_f32_e32 v93, v94, v94
	s_mov_b64 s[4:5], 0x40000
	v_max_f32_e32 v96, 0, v96
	v_max_f32_e32 v97, 0, v97
	v_max_f32_e32 v92, v98, v98
	v_max_f32_e32 v94, 0, v93
	v_max_f32_e32 v93, v99, v99
	v_max_f32_e32 v95, v95, v95
	v_lshl_add_u64 v[100:101], v[142:143], 0, s[4:5]
	v_pk_mul_f32 v[96:97], v[96:97], v[96:97]
	v_max_f32_e32 v92, 0, v92
	v_max_f32_e32 v93, 0, v93
	v_max_f32_e32 v95, 0, v95
	s_mov_b32 s4, 0x40000
	v_pk_mul_f32 v[98:99], v[92:93], v[92:93]
	v_pk_mul_f32 v[104:105], v[94:95], v[94:95]
	v_cvt_pk_bf16_f32 v92, v96, v97
	v_add_co_u32_e32 v96, vcc, s4, v142
	v_max_f32_e32 v84, v84, v84
	v_max_f32_e32 v85, v85, v85
	v_cvt_pk_bf16_f32 v93, v98, v99
	v_cvt_pk_bf16_f32 v94, v102, v103
	v_cvt_pk_bf16_f32 v95, v104, v105
	v_addc_co_u32_e32 v97, vcc, 0, v143, vcc
	v_max_f32_e32 v84, 0, v84
	v_max_f32_e32 v85, 0, v85
	global_store_dwordx4 v[96:97], v[92:95], off nt
	v_max_f32_e32 v88, v88, v88
	v_max_f32_e32 v89, v89, v89
	v_pk_mul_f32 v[92:93], v[84:85], v[84:85]
	v_max_f32_e32 v85, v86, v86
	v_max_f32_e32 v84, v90, v90
	v_max_f32_e32 v86, 0, v85
	v_max_f32_e32 v85, v91, v91
	v_max_f32_e32 v87, v87, v87
	v_max_f32_e32 v88, 0, v88
	v_max_f32_e32 v89, 0, v89
	v_max_f32_e32 v84, 0, v84
	v_max_f32_e32 v85, 0, v85
	v_max_f32_e32 v87, 0, v87
	v_pk_mul_f32 v[88:89], v[88:89], v[88:89]
	v_pk_mul_f32 v[90:91], v[84:85], v[84:85]
	v_pk_mul_f32 v[94:95], v[86:87], v[86:87]
	v_max_f32_e32 v76, v76, v76
	v_max_f32_e32 v77, v77, v77
	v_cvt_pk_bf16_f32 v84, v88, v89
	v_cvt_pk_bf16_f32 v85, v90, v91
	v_cvt_pk_bf16_f32 v86, v92, v93
	v_cvt_pk_bf16_f32 v87, v94, v95
	v_max_f32_e32 v76, 0, v76
	v_max_f32_e32 v77, 0, v77
	global_store_dwordx4 v[100:101], v[84:87], off offset:256 nt
	v_max_f32_e32 v80, v80, v80
	v_max_f32_e32 v81, v81, v81
	v_pk_mul_f32 v[86:87], v[76:77], v[76:77]
	v_max_f32_e32 v77, v78, v78
	s_mov_b64 s[4:5], 0x60000
	v_max_f32_e32 v80, 0, v80
	v_max_f32_e32 v81, 0, v81
	v_max_f32_e32 v76, v82, v82
	v_max_f32_e32 v78, 0, v77
	v_max_f32_e32 v77, v83, v83
	v_max_f32_e32 v79, v79, v79
	v_lshl_add_u64 v[84:85], v[142:143], 0, s[4:5]
	v_pk_mul_f32 v[80:81], v[80:81], v[80:81]
	v_max_f32_e32 v76, 0, v76
	v_max_f32_e32 v77, 0, v77
	v_max_f32_e32 v79, 0, v79
	s_mov_b32 s4, 0x60000
	v_pk_mul_f32 v[82:83], v[76:77], v[76:77]
	v_pk_mul_f32 v[88:89], v[78:79], v[78:79]
	v_cvt_pk_bf16_f32 v76, v80, v81
	v_add_co_u32_e32 v80, vcc, s4, v142
	v_max_f32_e32 v68, v68, v68
	v_max_f32_e32 v69, v69, v69
	v_cvt_pk_bf16_f32 v77, v82, v83
	v_cvt_pk_bf16_f32 v78, v86, v87
	v_cvt_pk_bf16_f32 v79, v88, v89
	v_addc_co_u32_e32 v81, vcc, 0, v143, vcc
	v_max_f32_e32 v68, 0, v68
	v_max_f32_e32 v69, 0, v69
	global_store_dwordx4 v[80:81], v[76:79], off nt
	v_max_f32_e32 v72, v72, v72
	v_max_f32_e32 v73, v73, v73
	v_pk_mul_f32 v[76:77], v[68:69], v[68:69]
	v_max_f32_e32 v69, v70, v70
	v_max_f32_e32 v68, v74, v74
	v_max_f32_e32 v70, 0, v69
	v_max_f32_e32 v69, v75, v75
	v_max_f32_e32 v71, v71, v71
	v_max_f32_e32 v72, 0, v72
	v_max_f32_e32 v73, 0, v73
	v_max_f32_e32 v68, 0, v68
	v_max_f32_e32 v69, 0, v69
	v_max_f32_e32 v71, 0, v71
	v_pk_mul_f32 v[72:73], v[72:73], v[72:73]
	v_pk_mul_f32 v[74:75], v[68:69], v[68:69]
	v_pk_mul_f32 v[78:79], v[70:71], v[70:71]
	v_max_f32_e32 v60, v60, v60
	v_max_f32_e32 v61, v61, v61
	v_cvt_pk_bf16_f32 v68, v72, v73
	v_cvt_pk_bf16_f32 v69, v74, v75
	v_cvt_pk_bf16_f32 v70, v76, v77
	v_cvt_pk_bf16_f32 v71, v78, v79
	v_max_f32_e32 v60, 0, v60
	v_max_f32_e32 v61, 0, v61
	global_store_dwordx4 v[84:85], v[68:71], off offset:256 nt
	v_max_f32_e32 v64, v64, v64
	v_max_f32_e32 v65, v65, v65
	v_pk_mul_f32 v[70:71], v[60:61], v[60:61]
	v_max_f32_e32 v61, v62, v62
	s_mov_b64 s[4:5], 0x100000
	v_max_f32_e32 v64, 0, v64
	v_max_f32_e32 v65, 0, v65
	v_max_f32_e32 v60, v66, v66
	v_max_f32_e32 v62, 0, v61
	v_max_f32_e32 v61, v67, v67
	v_max_f32_e32 v63, v63, v63
	v_lshl_add_u64 v[68:69], v[142:143], 0, s[4:5]
	v_pk_mul_f32 v[64:65], v[64:65], v[64:65]
	v_max_f32_e32 v60, 0, v60
	v_max_f32_e32 v61, 0, v61
	v_max_f32_e32 v63, 0, v63
	s_mov_b32 s4, 0x100000
	v_pk_mul_f32 v[66:67], v[60:61], v[60:61]
	v_pk_mul_f32 v[72:73], v[62:63], v[62:63]
	v_cvt_pk_bf16_f32 v60, v64, v65
	v_add_co_u32_e32 v64, vcc, s4, v142
	v_max_f32_e32 v52, v52, v52
	v_max_f32_e32 v53, v53, v53
	v_cvt_pk_bf16_f32 v61, v66, v67
	v_cvt_pk_bf16_f32 v62, v70, v71
	v_cvt_pk_bf16_f32 v63, v72, v73
	v_addc_co_u32_e32 v65, vcc, 0, v143, vcc
	v_max_f32_e32 v52, 0, v52
	v_max_f32_e32 v53, 0, v53
	global_store_dwordx4 v[64:65], v[60:63], off nt
	v_max_f32_e32 v56, v56, v56
	v_max_f32_e32 v57, v57, v57
	v_pk_mul_f32 v[60:61], v[52:53], v[52:53]
	v_max_f32_e32 v53, v54, v54
	v_max_f32_e32 v52, v58, v58
	v_max_f32_e32 v54, 0, v53
	v_max_f32_e32 v53, v59, v59
	v_max_f32_e32 v55, v55, v55
	v_max_f32_e32 v56, 0, v56
	v_max_f32_e32 v57, 0, v57
	v_max_f32_e32 v52, 0, v52
	v_max_f32_e32 v53, 0, v53
	v_max_f32_e32 v55, 0, v55
	v_pk_mul_f32 v[56:57], v[56:57], v[56:57]
	v_pk_mul_f32 v[58:59], v[52:53], v[52:53]
	v_pk_mul_f32 v[62:63], v[54:55], v[54:55]
	v_max_f32_e32 v44, v44, v44
	v_max_f32_e32 v45, v45, v45
	v_cvt_pk_bf16_f32 v52, v56, v57
	v_cvt_pk_bf16_f32 v53, v58, v59
	v_cvt_pk_bf16_f32 v54, v60, v61
	v_cvt_pk_bf16_f32 v55, v62, v63
	v_max_f32_e32 v44, 0, v44
	v_max_f32_e32 v45, 0, v45
	global_store_dwordx4 v[68:69], v[52:55], off offset:256 nt
	v_max_f32_e32 v48, v48, v48
	v_max_f32_e32 v49, v49, v49
	v_pk_mul_f32 v[54:55], v[44:45], v[44:45]
	v_max_f32_e32 v45, v46, v46
	s_mov_b64 s[4:5], 0x120000
	v_max_f32_e32 v48, 0, v48
	v_max_f32_e32 v49, 0, v49
	v_max_f32_e32 v44, v50, v50
	v_max_f32_e32 v46, 0, v45
	v_max_f32_e32 v45, v51, v51
	v_max_f32_e32 v47, v47, v47
	v_lshl_add_u64 v[52:53], v[142:143], 0, s[4:5]
	v_pk_mul_f32 v[48:49], v[48:49], v[48:49]
	v_max_f32_e32 v44, 0, v44
	v_max_f32_e32 v45, 0, v45
	v_max_f32_e32 v47, 0, v47
	s_mov_b32 s4, 0x120000
	v_pk_mul_f32 v[50:51], v[44:45], v[44:45]
	v_pk_mul_f32 v[56:57], v[46:47], v[46:47]
	v_cvt_pk_bf16_f32 v44, v48, v49
	v_add_co_u32_e32 v48, vcc, s4, v142
	v_max_f32_e32 v36, v36, v36
	v_max_f32_e32 v37, v37, v37
	v_cvt_pk_bf16_f32 v45, v50, v51
	v_cvt_pk_bf16_f32 v46, v54, v55
	v_cvt_pk_bf16_f32 v47, v56, v57
	v_addc_co_u32_e32 v49, vcc, 0, v143, vcc
	v_max_f32_e32 v36, 0, v36
	v_max_f32_e32 v37, 0, v37
	global_store_dwordx4 v[48:49], v[44:47], off nt
	v_max_f32_e32 v40, v40, v40
	v_max_f32_e32 v41, v41, v41
	v_pk_mul_f32 v[44:45], v[36:37], v[36:37]
	v_max_f32_e32 v37, v38, v38
	v_max_f32_e32 v36, v42, v42
	v_max_f32_e32 v38, 0, v37
	v_max_f32_e32 v37, v43, v43
	v_max_f32_e32 v39, v39, v39
	v_max_f32_e32 v40, 0, v40
	v_max_f32_e32 v41, 0, v41
	v_max_f32_e32 v36, 0, v36
	v_max_f32_e32 v37, 0, v37
	v_max_f32_e32 v39, 0, v39
	v_pk_mul_f32 v[40:41], v[40:41], v[40:41]
	v_pk_mul_f32 v[42:43], v[36:37], v[36:37]
	v_pk_mul_f32 v[46:47], v[38:39], v[38:39]
	v_max_f32_e32 v28, v28, v28
	v_max_f32_e32 v29, v29, v29
	v_cvt_pk_bf16_f32 v36, v40, v41
	v_cvt_pk_bf16_f32 v37, v42, v43
	v_cvt_pk_bf16_f32 v38, v44, v45
	v_cvt_pk_bf16_f32 v39, v46, v47
	v_max_f32_e32 v28, 0, v28
	v_max_f32_e32 v29, 0, v29
	global_store_dwordx4 v[52:53], v[36:39], off offset:256 nt
	v_max_f32_e32 v32, v32, v32
	v_max_f32_e32 v33, v33, v33
	v_pk_mul_f32 v[38:39], v[28:29], v[28:29]
	v_max_f32_e32 v29, v30, v30
	s_mov_b64 s[4:5], 0x140000
	v_max_f32_e32 v32, 0, v32
	v_max_f32_e32 v33, 0, v33
	v_max_f32_e32 v28, v34, v34
	v_max_f32_e32 v30, 0, v29
	v_max_f32_e32 v29, v35, v35
	v_max_f32_e32 v31, v31, v31
	v_lshl_add_u64 v[36:37], v[142:143], 0, s[4:5]
	v_pk_mul_f32 v[32:33], v[32:33], v[32:33]
	v_max_f32_e32 v28, 0, v28
	v_max_f32_e32 v29, 0, v29
	v_max_f32_e32 v31, 0, v31
	s_mov_b32 s4, 0x140000
	v_pk_mul_f32 v[34:35], v[28:29], v[28:29]
	v_pk_mul_f32 v[40:41], v[30:31], v[30:31]
	v_cvt_pk_bf16_f32 v28, v32, v33
	v_add_co_u32_e32 v32, vcc, s4, v142
	v_max_f32_e32 v20, v20, v20
	v_max_f32_e32 v21, v21, v21
	v_cvt_pk_bf16_f32 v29, v34, v35
	v_cvt_pk_bf16_f32 v30, v38, v39
	v_cvt_pk_bf16_f32 v31, v40, v41
	v_addc_co_u32_e32 v33, vcc, 0, v143, vcc
	v_max_f32_e32 v20, 0, v20
	v_max_f32_e32 v21, 0, v21
	global_store_dwordx4 v[32:33], v[28:31], off nt
	v_max_f32_e32 v24, v24, v24
	v_max_f32_e32 v25, v25, v25
	v_pk_mul_f32 v[28:29], v[20:21], v[20:21]
	v_max_f32_e32 v21, v22, v22
	v_max_f32_e32 v20, v26, v26
	v_max_f32_e32 v22, 0, v21
	v_max_f32_e32 v21, v27, v27
	v_max_f32_e32 v23, v23, v23
	v_max_f32_e32 v24, 0, v24
	v_max_f32_e32 v25, 0, v25
	v_max_f32_e32 v20, 0, v20
	v_max_f32_e32 v21, 0, v21
	v_max_f32_e32 v23, 0, v23
	v_pk_mul_f32 v[24:25], v[24:25], v[24:25]
	v_pk_mul_f32 v[26:27], v[20:21], v[20:21]
	v_pk_mul_f32 v[30:31], v[22:23], v[22:23]
	v_max_f32_e32 v12, v12, v12
	v_max_f32_e32 v13, v13, v13
	v_cvt_pk_bf16_f32 v20, v24, v25
	v_cvt_pk_bf16_f32 v21, v26, v27
	v_cvt_pk_bf16_f32 v22, v28, v29
	v_cvt_pk_bf16_f32 v23, v30, v31
	v_max_f32_e32 v12, 0, v12
	v_max_f32_e32 v13, 0, v13
	global_store_dwordx4 v[36:37], v[20:23], off offset:256 nt
	v_max_f32_e32 v16, v16, v16
	v_max_f32_e32 v17, v17, v17
	v_pk_mul_f32 v[22:23], v[12:13], v[12:13]
	v_max_f32_e32 v13, v14, v14
	s_mov_b64 s[4:5], 0x160000
	v_max_f32_e32 v16, 0, v16
	v_max_f32_e32 v17, 0, v17
	v_max_f32_e32 v12, v18, v18
	v_max_f32_e32 v14, 0, v13
	v_max_f32_e32 v13, v19, v19
	v_max_f32_e32 v15, v15, v15
	v_lshl_add_u64 v[20:21], v[142:143], 0, s[4:5]
	v_pk_mul_f32 v[16:17], v[16:17], v[16:17]
	v_max_f32_e32 v12, 0, v12
	v_max_f32_e32 v13, 0, v13
	v_max_f32_e32 v15, 0, v15
	s_mov_b32 s4, 0x160000
	v_pk_mul_f32 v[18:19], v[12:13], v[12:13]
	v_pk_mul_f32 v[24:25], v[14:15], v[14:15]
	v_cvt_pk_bf16_f32 v12, v16, v17
	v_add_co_u32_e32 v16, vcc, s4, v142
	v_max_f32_e32 v4, v4, v4
	v_max_f32_e32 v5, v5, v5
	v_cvt_pk_bf16_f32 v13, v18, v19
	v_cvt_pk_bf16_f32 v14, v22, v23
	v_cvt_pk_bf16_f32 v15, v24, v25
	v_addc_co_u32_e32 v17, vcc, 0, v143, vcc
	v_max_f32_e32 v4, 0, v4
	v_max_f32_e32 v5, 0, v5
	global_store_dwordx4 v[16:17], v[12:15], off nt
	v_max_f32_e32 v8, v8, v8
	v_max_f32_e32 v9, v9, v9
	v_pk_mul_f32 v[12:13], v[4:5], v[4:5]
	v_max_f32_e32 v5, v6, v6
	v_max_f32_e32 v4, v10, v10
	v_max_f32_e32 v6, 0, v5
	v_max_f32_e32 v5, v11, v11
	v_max_f32_e32 v7, v7, v7
	v_max_f32_e32 v8, 0, v8
	v_max_f32_e32 v9, 0, v9
	v_max_f32_e32 v4, 0, v4
	v_max_f32_e32 v5, 0, v5
	v_max_f32_e32 v7, 0, v7
	v_pk_mul_f32 v[8:9], v[8:9], v[8:9]
	v_pk_mul_f32 v[10:11], v[4:5], v[4:5]
	v_pk_mul_f32 v[14:15], v[6:7], v[6:7]
	v_cvt_pk_bf16_f32 v4, v8, v9
	v_cvt_pk_bf16_f32 v5, v10, v11
	v_cvt_pk_bf16_f32 v6, v12, v13
	v_cvt_pk_bf16_f32 v7, v14, v15
	s_andn2_b64 vcc, exec, s[6:7]
	s_mov_b64 s[4:5], -1
	s_mov_b32 s54, 0xe10000
	s_movk_i32 s55, 0x1fff
	global_store_dwordx4 v[20:21], v[4:7], off offset:256 nt
	s_cbranch_vccnz .LBB0_101
	s_andn2_b64 vcc, exec, s[8:9]
	s_cbranch_vccnz .LBB0_100
	s_barrier
	s_branch .LBB0_100
